# alias-safe set of cache invalidates: after P1, P3 and P5 (workspace regions are time-shared: W_in/TF, QA+GQKV/MERGED); barrier after P1 is XCD-local only in layer 0 (layer-1 weights are converted in P
# baseline (speedup 1.0000x reference)
.LBB0_375:
	s_lshl_b32 s6, s6, 6
	s_add_i32 s82, s6, 0x500
	s_lshl_b64 s[8:9], s[82:83], 2
	s_add_u32 s8, s42, s8
	s_addc_u32 s9, s43, s9
	v_mov_b64_e32 v[4:5], s[8:9]
	flat_atomic_add v3, v[4:5], v228 sc0
	v_cvt_f32_u32_e32 v1, v2
	v_sub_u32_e32 v4, 0, v2
	v_rcp_iflag_f32_e32 v1, v1
	s_nop 0
	v_mul_f32_e32 v1, 0x4f7ffffe, v1
	v_cvt_u32_f32_e32 v1, v1
	v_mul_lo_u32 v4, v4, v1
	v_mul_hi_u32 v4, v1, v4
	v_add_u32_e32 v1, v1, v4
	s_waitcnt vmcnt(0) lgkmcnt(0)
	v_mul_hi_u32 v1, v3, v1
	v_mul_lo_u32 v4, v1, v2
	v_sub_u32_e32 v4, v3, v4
	v_cmp_ge_u32_e32 vcc, v4, v2
	v_add_u32_e32 v5, 1, v1
	s_nop 0
	v_cndmask_b32_e32 v1, v1, v5, vcc
	v_sub_u32_e32 v5, v4, v2
	v_cndmask_b32_e32 v4, v4, v5, vcc
	v_cmp_ge_u32_e32 vcc, v4, v2
	v_add_u32_e32 v4, 1, v1
	s_nop 0
	v_cndmask_b32_e32 v1, v1, v4, vcc
	v_add_u32_e32 v4, 1, v3
	v_mad_u64_u32 v[2:3], s[8:9], v2, v1, v[2:3]
	v_cmp_ne_u32_e32 vcc, v4, v2
	s_and_saveexec_b64 s[8:9], vcc
	s_xor_b64 s[8:9], exec, s[8:9]
	s_cbranch_execz .LBB0_388
	s_cmp_eq_u32 s100, 0
	s_cbranch_scc1 .Lnf_1
	s_cmp_lg_u32 s101, 1
	s_cbranch_scc1 .Lnf_1
	s_add_i32 s82, s6, 0x900
	s_lshl_b64 s[10:11], s[82:83], 2
	s_add_u32 s10, s42, s10
	s_addc_u32 s11, s43, s11
	v_mov_b64_e32 v[2:3], s[10:11]

.LBB0_388:
	s_andn2_saveexec_b64 s[8:9], s[8:9]
	s_cbranch_execz .LBB0_404
	s_cmp_eq_u32 s100, 0
	s_cbranch_scc1 .Lfl_1
	s_cmp_lg_u32 s101, 1
	s_cbranch_scc1 .Lfl_1
	s_add_i32 s82, s6, 0x900
	s_lshl_b64 s[10:11], s[82:83], 2
	s_add_u32 s10, s42, s10
	s_addc_u32 s11, s43, s11
	v_mov_b64_e32 v[0:1], s[10:11]
	flat_atomic_add v[0:1], v228
	buffer_inv sc1
	s_waitcnt vmcnt(0)
	s_branch .LBB0_404
